# deferred out-proj sample tiles: counted hand-off kept, L2 writeback and invalidate dropped (producers and consumers share one XCD L2)
# speedup vs baseline: 1.0063x; 1.0063x over previous
.Lp3_pass2_done:
	s_and_saveexec_b64 s[0:1], s[96:97]
	s_cbranch_execz .Lp3_pass2_skip
	v_mov_b32_e32 v2, 0
	v_mov_b32_e32 v3, 1
	global_atomic_add v2, v3, s[80:81] offset:32

.Lp4_ok:
.Lp4_nowait:
	s_ashr_i32 s23, s22, 31
	s_lshl_b64 s[24:25], s[22:23], 19
	s_add_u32 s24, s40, s24
	s_addc_u32 s25, s41, s25
	s_and_b64 s[26:27], s[4:5], exec
	s_cselect_b32 s23, s25, s29
	s_cselect_b32 s52, s24, s28
	s_ashr_i32 s21, s20, 31
	s_lshl_b64 s[26:27], s[20:21], 19
	s_add_u32 s26, s3, s26
	s_addc_u32 s27, s17, s27
	s_and_b64 s[38:39], s[4:5], exec
	s_cselect_b32 s21, s27, s31
	s_cselect_b32 s53, s26, s30
	s_cselect_b32 s38, s22, s0
	v_lshl_add_u32 v248, s38, 8, v1
	s_add_u32 s28, s28, 0x40080
	s_addc_u32 s29, s29, 0
	s_add_u32 s54, s30, 0x100
	s_addc_u32 s55, s31, 0
	s_mov_b32 s56, -2
	ds_read_b128 v[146:149], v154
	ds_read_b128 v[158:161], v154 offset:1024
	ds_read_b128 v[162:165], v154 offset:2048
	ds_read_b128 v[166:169], v154 offset:3072
	ds_read_b128 v[172:175], v155
	ds_read_b128 v[176:179], v155 offset:1024
	ds_read_b128 v[180:183], v155 offset:2048
	ds_read_b128 v[184:187], v155 offset:3072
	s_add_u32 s30, s28, 0xfffc0080
	s_addc_u32 s31, s29, -1
	s_cmp_eq_u32 s56, 12
	s_cselect_b32 s39, s23, s31
	s_cselect_b32 s38, s52, s30
	s_cselect_b32 s31, s21, s55
	s_cselect_b32 s30, s53, s54
	v_lshl_add_u64 v[150:151], s[28:29], 0, v[138:139]
	s_add_i32 m0, s44, 0xc000
	ds_read_b128 v[188:191], v156
	ds_read_b128 v[192:195], v156 offset:1024
	ds_read_b128 v[196:199], v156 offset:2048
	ds_read_b128 v[200:203], v156 offset:3072
	ds_read_b128 v[204:207], v156 offset:4096
	ds_read_b128 v[212:215], v156 offset:5120
	ds_read_b128 v[216:219], v156 offset:6144
	ds_read_b128 v[220:223], v156 offset:7168
	global_load_lds_dwordx4 v[150:151], off
	v_lshl_add_u64 v[150:151], s[28:29], 0, v[140:141]
	s_add_i32 m0, s44, 0xe000
	s_nop 0
	global_load_lds_dwordx4 v[150:151], off
	s_waitcnt vmcnt(22)
	s_waitcnt lgkmcnt(0)
	s_barrier
	s_setprio 1
	s_waitcnt lgkmcnt(0)
	v_mfma_f32_16x16x32_bf16 v[118:121], v[146:149], v[188:191], 0
	v_mfma_f32_16x16x32_bf16 v[126:129], v[162:165], v[188:191], 0
	v_mfma_f32_16x16x32_bf16 v[110:113], v[146:149], v[196:199], 0
	v_mfma_f32_16x16x32_bf16 v[106:109], v[162:165], v[196:199], 0
	v_mfma_f32_16x16x32_bf16 v[86:89], v[146:149], v[204:207], 0
	v_mfma_f32_16x16x32_bf16 v[94:97], v[162:165], v[204:207], 0
	v_mfma_f32_16x16x32_bf16 v[78:81], v[146:149], v[216:219], 0
	v_mfma_f32_16x16x32_bf16 v[74:77], v[162:165], v[216:219], 0
	v_mfma_f32_16x16x32_bf16 v[118:121], v[158:161], v[192:195], v[118:121]
	v_mfma_f32_16x16x32_bf16 v[126:129], v[166:169], v[192:195], v[126:129]
	v_mfma_f32_16x16x32_bf16 v[110:113], v[158:161], v[200:203], v[110:113]
	v_mfma_f32_16x16x32_bf16 v[106:109], v[166:169], v[200:203], v[106:109]
	v_mfma_f32_16x16x32_bf16 v[86:89], v[158:161], v[212:215], v[86:89]
	v_mfma_f32_16x16x32_bf16 v[94:97], v[166:169], v[212:215], v[94:97]
	v_mfma_f32_16x16x32_bf16 v[78:81], v[158:161], v[220:223], v[78:81]
	v_mfma_f32_16x16x32_bf16 v[74:77], v[166:169], v[220:223], v[74:77]
	s_setprio 0
	s_setprio 1
	v_mfma_f32_16x16x32_bf16 v[114:117], v[172:175], v[188:191], 0
	v_mfma_f32_16x16x32_bf16 v[122:125], v[180:183], v[188:191], 0
	v_mfma_f32_16x16x32_bf16 v[102:105], v[172:175], v[196:199], 0
	v_mfma_f32_16x16x32_bf16 v[98:101], v[180:183], v[196:199], 0
	v_mfma_f32_16x16x32_bf16 v[82:85], v[172:175], v[204:207], 0
	v_mfma_f32_16x16x32_bf16 v[90:93], v[180:183], v[204:207], 0
	v_mfma_f32_16x16x32_bf16 v[70:73], v[172:175], v[216:219], 0
	v_mfma_f32_16x16x32_bf16 v[66:69], v[180:183], v[216:219], 0
	v_mfma_f32_16x16x32_bf16 v[114:117], v[176:179], v[192:195], v[114:117]
	v_mfma_f32_16x16x32_bf16 v[122:125], v[184:187], v[192:195], v[122:125]
	v_mfma_f32_16x16x32_bf16 v[102:105], v[176:179], v[200:203], v[102:105]
	v_mfma_f32_16x16x32_bf16 v[98:101], v[184:187], v[200:203], v[98:101]
	v_mfma_f32_16x16x32_bf16 v[82:85], v[176:179], v[212:215], v[82:85]
	v_mfma_f32_16x16x32_bf16 v[90:93], v[184:187], v[212:215], v[90:93]
	v_mfma_f32_16x16x32_bf16 v[70:73], v[176:179], v[220:223], v[70:73]
	v_mfma_f32_16x16x32_bf16 v[66:69], v[184:187], v[220:223], v[66:69]
	s_setprio 0
	s_barrier
	s_add_i32 s42, s36, s19
	v_lshl_add_u64 v[150:151], s[30:31], 0, v[134:135]
	s_mov_b32 m0, s42
	ds_read_b128 v[188:191], v156 offset:16384
	ds_read_b128 v[192:195], v156 offset:17408
	ds_read_b128 v[196:199], v156 offset:18432
	ds_read_b128 v[200:203], v156 offset:19456
	ds_read_b128 v[204:207], v156 offset:20480
	ds_read_b128 v[212:215], v156 offset:21504
	ds_read_b128 v[216:219], v156 offset:22528
	ds_read_b128 v[220:223], v156 offset:23552
	global_load_lds_dwordx4 v[150:151], off
	s_add_i32 m0, s42, 0x2000
	s_add_u32 s42, s30, 0x40000
	v_lshl_add_u64 v[208:209], s[30:31], 0, v[130:131]
	s_addc_u32 s43, s31, 0
	s_add_i32 s57, s37, s19
	global_load_lds_dwordx4 v[208:209], off
	v_lshl_add_u64 v[224:225], s[42:43], 0, v[134:135]
	s_mov_b32 m0, s57
	v_lshl_add_u64 v[226:227], s[38:39], 0, v[132:133]
	global_load_lds_dwordx4 v[224:225], off
	v_lshl_add_u64 v[224:225], s[42:43], 0, v[130:131]
	s_add_i32 m0, s57, 0x2000
	s_nop 0
	global_load_lds_dwordx4 v[224:225], off
	v_lshl_add_u64 v[224:225], s[38:39], 0, v[136:137]
	s_mov_b32 m0, s44
	s_nop 0
	global_load_lds_dwordx4 v[224:225], off
	s_mov_b32 m0, s45
	s_nop 0
	global_load_lds_dwordx4 v[226:227], off
	s_waitcnt vmcnt(22)
	s_waitcnt lgkmcnt(0)
	s_barrier
	s_setprio 1
	s_waitcnt lgkmcnt(0)
	v_mfma_f32_16x16x32_bf16 v[58:61], v[146:149], v[188:191], 0
	v_mfma_f32_16x16x32_bf16 v[62:65], v[162:165], v[188:191], 0
	v_mfma_f32_16x16x32_bf16 v[46:49], v[146:149], v[196:199], 0
	v_mfma_f32_16x16x32_bf16 v[42:45], v[162:165], v[196:199], 0
	v_mfma_f32_16x16x32_bf16 v[22:25], v[146:149], v[204:207], 0
	v_mfma_f32_16x16x32_bf16 v[30:33], v[162:165], v[204:207], 0
	v_mfma_f32_16x16x32_bf16 v[14:17], v[146:149], v[216:219], 0
	v_mfma_f32_16x16x32_bf16 v[10:13], v[162:165], v[216:219], 0
	v_mfma_f32_16x16x32_bf16 v[58:61], v[158:161], v[192:195], v[58:61]
	v_mfma_f32_16x16x32_bf16 v[62:65], v[166:169], v[192:195], v[62:65]
	v_mfma_f32_16x16x32_bf16 v[46:49], v[158:161], v[200:203], v[46:49]
	v_mfma_f32_16x16x32_bf16 v[42:45], v[166:169], v[200:203], v[42:45]
	v_mfma_f32_16x16x32_bf16 v[22:25], v[158:161], v[212:215], v[22:25]
	v_mfma_f32_16x16x32_bf16 v[30:33], v[166:169], v[212:215], v[30:33]
	v_mfma_f32_16x16x32_bf16 v[14:17], v[158:161], v[220:223], v[14:17]
	v_mfma_f32_16x16x32_bf16 v[10:13], v[166:169], v[220:223], v[10:13]
	s_setprio 0
	s_setprio 1
	v_mfma_f32_16x16x32_bf16 v[50:53], v[172:175], v[188:191], 0
	v_mfma_f32_16x16x32_bf16 v[54:57], v[180:183], v[188:191], 0
	v_mfma_f32_16x16x32_bf16 v[38:41], v[172:175], v[196:199], 0
	v_mfma_f32_16x16x32_bf16 v[34:37], v[180:183], v[196:199], 0
	v_mfma_f32_16x16x32_bf16 v[18:21], v[172:175], v[204:207], 0
	v_mfma_f32_16x16x32_bf16 v[26:29], v[180:183], v[204:207], 0
	v_mfma_f32_16x16x32_bf16 v[6:9], v[172:175], v[216:219], 0
	v_mfma_f32_16x16x32_bf16 v[2:5], v[180:183], v[216:219], 0
	v_mfma_f32_16x16x32_bf16 v[50:53], v[176:179], v[192:195], v[50:53]
	v_mfma_f32_16x16x32_bf16 v[54:57], v[184:187], v[192:195], v[54:57]
	v_mfma_f32_16x16x32_bf16 v[38:41], v[176:179], v[200:203], v[38:41]
	v_mfma_f32_16x16x32_bf16 v[34:37], v[184:187], v[200:203], v[34:37]
	v_mfma_f32_16x16x32_bf16 v[18:21], v[176:179], v[212:215], v[18:21]
	v_mfma_f32_16x16x32_bf16 v[26:29], v[184:187], v[212:215], v[26:29]
	v_mfma_f32_16x16x32_bf16 v[6:9], v[176:179], v[220:223], v[6:9]
	v_mfma_f32_16x16x32_bf16 v[2:5], v[184:187], v[220:223], v[2:5]
	s_setprio 0
	s_barrier
	s_add_i32 s42, 0, 0x18000
	v_add_u32_e32 v157, s42, v152
	s_add_i32 s43, 0, 0x1c000
	ds_read_b128 v[146:149], v157
	ds_read_b128 v[158:161], v157 offset:1024
	ds_read_b128 v[162:165], v157 offset:2048
	ds_read_b128 v[166:169], v157 offset:3072
	v_add_u32_e32 v157, s43, v152
	ds_read_b128 v[172:175], v157
	ds_read_b128 v[176:179], v157 offset:1024
	ds_read_b128 v[180:183], v157 offset:2048
	ds_read_b128 v[184:187], v157 offset:3072
	s_add_u32 s38, s38, 0x40000
	s_addc_u32 s39, s39, 0
	s_mov_b32 m0, s33
	v_lshl_add_u64 v[228:229], s[38:39], 0, v[136:137]
	ds_read_b128 v[188:191], v156 offset:32768
	ds_read_b128 v[192:195], v156 offset:33792
	ds_read_b128 v[196:199], v156 offset:34816
	ds_read_b128 v[200:203], v156 offset:35840
	ds_read_b128 v[204:207], v156 offset:36864
	ds_read_b128 v[212:215], v156 offset:37888
	ds_read_b128 v[216:219], v156 offset:38912
	ds_read_b128 v[220:223], v156 offset:39936
	global_load_lds_dwordx4 v[228:229], off
	v_lshl_add_u64 v[228:229], s[38:39], 0, v[132:133]
	s_mov_b32 m0, s46
	s_nop 0
	global_load_lds_dwordx4 v[228:229], off
	s_waitcnt vmcnt(8)
	s_waitcnt lgkmcnt(0)
	s_barrier
	s_setprio 1
	s_waitcnt lgkmcnt(0)
	v_mfma_f32_16x16x32_bf16 v[118:121], v[146:149], v[188:191], v[118:121]
	v_mfma_f32_16x16x32_bf16 v[126:129], v[162:165], v[188:191], v[126:129]
	v_mfma_f32_16x16x32_bf16 v[110:113], v[146:149], v[196:199], v[110:113]
	v_mfma_f32_16x16x32_bf16 v[106:109], v[162:165], v[196:199], v[106:109]
	v_mfma_f32_16x16x32_bf16 v[86:89], v[146:149], v[204:207], v[86:89]
	v_mfma_f32_16x16x32_bf16 v[94:97], v[162:165], v[204:207], v[94:97]
	v_mfma_f32_16x16x32_bf16 v[78:81], v[146:149], v[216:219], v[78:81]
	v_mfma_f32_16x16x32_bf16 v[74:77], v[162:165], v[216:219], v[74:77]
	v_mfma_f32_16x16x32_bf16 v[118:121], v[158:161], v[192:195], v[118:121]
	v_mfma_f32_16x16x32_bf16 v[126:129], v[166:169], v[192:195], v[126:129]
	v_mfma_f32_16x16x32_bf16 v[110:113], v[158:161], v[200:203], v[110:113]
	v_mfma_f32_16x16x32_bf16 v[106:109], v[166:169], v[200:203], v[106:109]
	v_mfma_f32_16x16x32_bf16 v[86:89], v[158:161], v[212:215], v[86:89]
	v_mfma_f32_16x16x32_bf16 v[94:97], v[166:169], v[212:215], v[94:97]
	v_mfma_f32_16x16x32_bf16 v[78:81], v[158:161], v[220:223], v[78:81]
	v_mfma_f32_16x16x32_bf16 v[74:77], v[166:169], v[220:223], v[74:77]
	s_setprio 0
	s_setprio 1
	v_mfma_f32_16x16x32_bf16 v[114:117], v[172:175], v[188:191], v[114:117]
	v_mfma_f32_16x16x32_bf16 v[122:125], v[180:183], v[188:191], v[122:125]
	v_mfma_f32_16x16x32_bf16 v[102:105], v[172:175], v[196:199], v[102:105]
	v_mfma_f32_16x16x32_bf16 v[98:101], v[180:183], v[196:199], v[98:101]
	v_mfma_f32_16x16x32_bf16 v[82:85], v[172:175], v[204:207], v[82:85]
	v_mfma_f32_16x16x32_bf16 v[90:93], v[180:183], v[204:207], v[90:93]
	v_mfma_f32_16x16x32_bf16 v[70:73], v[172:175], v[216:219], v[70:73]
	v_mfma_f32_16x16x32_bf16 v[66:69], v[180:183], v[216:219], v[66:69]
	v_mfma_f32_16x16x32_bf16 v[114:117], v[176:179], v[192:195], v[114:117]
	v_mfma_f32_16x16x32_bf16 v[122:125], v[184:187], v[192:195], v[122:125]
	v_mfma_f32_16x16x32_bf16 v[102:105], v[176:179], v[200:203], v[102:105]
	v_mfma_f32_16x16x32_bf16 v[98:101], v[184:187], v[200:203], v[98:101]
	v_mfma_f32_16x16x32_bf16 v[82:85], v[176:179], v[212:215], v[82:85]
	v_mfma_f32_16x16x32_bf16 v[90:93], v[184:187], v[212:215], v[90:93]
	v_mfma_f32_16x16x32_bf16 v[70:73], v[176:179], v[220:223], v[70:73]
	v_mfma_f32_16x16x32_bf16 v[66:69], v[184:187], v[220:223], v[66:69]
	s_setprio 0
	s_barrier
	s_add_i32 s38, s42, s19
	v_lshl_add_u64 v[150:151], v[150:151], 0, s[12:13]
	s_mov_b32 m0, s38
	ds_read_b128 v[188:191], v156 offset:49152
	ds_read_b128 v[192:195], v156 offset:50176
	ds_read_b128 v[196:199], v156 offset:51200
	ds_read_b128 v[200:203], v156 offset:52224
	ds_read_b128 v[204:207], v156 offset:53248
	ds_read_b128 v[212:215], v156 offset:54272
	ds_read_b128 v[216:219], v156 offset:55296
	ds_read_b128 v[220:223], v156 offset:56320
	global_load_lds_dwordx4 v[150:151], off
	s_add_i32 m0, s38, 0x2000
	s_add_u32 s30, s30, 0x40080
	v_lshl_add_u64 v[150:151], v[208:209], 0, s[12:13]
	s_addc_u32 s31, s31, 0
	s_add_i32 s38, s43, s19
	global_load_lds_dwordx4 v[150:151], off
	v_lshl_add_u64 v[150:151], s[30:31], 0, v[134:135]
	s_mov_b32 m0, s38
	s_nop 0
	global_load_lds_dwordx4 v[150:151], off
	v_lshl_add_u64 v[150:151], s[30:31], 0, v[130:131]
	s_add_i32 m0, s38, 0x2000
	s_nop 0
	global_load_lds_dwordx4 v[150:151], off
	v_lshl_add_u64 v[150:151], v[224:225], 0, s[12:13]
	s_mov_b32 m0, s48
	s_nop 0
	global_load_lds_dwordx4 v[150:151], off
	v_lshl_add_u64 v[150:151], v[226:227], 0, s[12:13]
	s_mov_b32 m0, s49
	s_nop 0
	global_load_lds_dwordx4 v[150:151], off
	s_waitcnt vmcnt(8)
	s_waitcnt lgkmcnt(0)
	s_barrier
	s_setprio 1
	s_waitcnt lgkmcnt(0)
	v_mfma_f32_16x16x32_bf16 v[58:61], v[146:149], v[188:191], v[58:61]
	v_mfma_f32_16x16x32_bf16 v[62:65], v[162:165], v[188:191], v[62:65]
	v_mfma_f32_16x16x32_bf16 v[46:49], v[146:149], v[196:199], v[46:49]
	v_mfma_f32_16x16x32_bf16 v[42:45], v[162:165], v[196:199], v[42:45]
	v_mfma_f32_16x16x32_bf16 v[22:25], v[146:149], v[204:207], v[22:25]
	v_mfma_f32_16x16x32_bf16 v[30:33], v[162:165], v[204:207], v[30:33]
	v_mfma_f32_16x16x32_bf16 v[14:17], v[146:149], v[216:219], v[14:17]
	v_mfma_f32_16x16x32_bf16 v[10:13], v[162:165], v[216:219], v[10:13]
	v_mfma_f32_16x16x32_bf16 v[58:61], v[158:161], v[192:195], v[58:61]
	v_mfma_f32_16x16x32_bf16 v[62:65], v[166:169], v[192:195], v[62:65]
	v_mfma_f32_16x16x32_bf16 v[46:49], v[158:161], v[200:203], v[46:49]
	v_mfma_f32_16x16x32_bf16 v[42:45], v[166:169], v[200:203], v[42:45]
	v_mfma_f32_16x16x32_bf16 v[22:25], v[158:161], v[212:215], v[22:25]
	v_mfma_f32_16x16x32_bf16 v[30:33], v[166:169], v[212:215], v[30:33]
	v_mfma_f32_16x16x32_bf16 v[14:17], v[158:161], v[220:223], v[14:17]
	v_mfma_f32_16x16x32_bf16 v[10:13], v[166:169], v[220:223], v[10:13]
	s_setprio 0
	s_setprio 1
	v_mfma_f32_16x16x32_bf16 v[50:53], v[172:175], v[188:191], v[50:53]
	v_mfma_f32_16x16x32_bf16 v[54:57], v[180:183], v[188:191], v[54:57]
	v_mfma_f32_16x16x32_bf16 v[38:41], v[172:175], v[196:199], v[38:41]
	v_mfma_f32_16x16x32_bf16 v[34:37], v[180:183], v[196:199], v[34:37]
	v_mfma_f32_16x16x32_bf16 v[18:21], v[172:175], v[204:207], v[18:21]
	v_mfma_f32_16x16x32_bf16 v[26:29], v[180:183], v[204:207], v[26:29]
	v_mfma_f32_16x16x32_bf16 v[6:9], v[172:175], v[216:219], v[6:9]
	v_mfma_f32_16x16x32_bf16 v[2:5], v[180:183], v[216:219], v[2:5]
	v_mfma_f32_16x16x32_bf16 v[50:53], v[176:179], v[192:195], v[50:53]
	v_mfma_f32_16x16x32_bf16 v[54:57], v[184:187], v[192:195], v[54:57]
	v_mfma_f32_16x16x32_bf16 v[38:41], v[176:179], v[200:203], v[38:41]
	v_mfma_f32_16x16x32_bf16 v[34:37], v[184:187], v[200:203], v[34:37]
	v_mfma_f32_16x16x32_bf16 v[18:21], v[176:179], v[212:215], v[18:21]
	v_mfma_f32_16x16x32_bf16 v[26:29], v[184:187], v[212:215], v[26:29]
	v_mfma_f32_16x16x32_bf16 v[6:9], v[176:179], v[220:223], v[6:9]
	v_mfma_f32_16x16x32_bf16 v[2:5], v[184:187], v[220:223], v[2:5]
	s_setprio 0
	s_barrier
	s_add_i32 s56, s56, 2
	s_add_u32 s28, s28, 0x100
	s_addc_u32 s29, s29, 0
	s_add_u32 s54, s54, 0x100
	s_addc_u32 s55, s55, 0
